# phase-2 row loop: invariant gain/conv-weight loads hoisted, conv window loads batched; lru scan pass-1 loads batched
# speedup vs baseline: 1.0193x; 1.0193x over previous
; __global__ void __launch_bounds__(512, 2) trunk_fwd(Params p) {
;     ...
;             const float* qn_g = kp->in[15] + lq * 384; const float* kvn_g = kp->in[17] + lq * 256;
;             const float* cw = kp->in[20] + (size_t)lq * 4 * 256; const float* cb = kp->in[21] + lq * 256; const float* stc = kp->in[5] + (size_t)lq * DBATCH * 3 * 256;
;             const h16* __restrict__ z = WSP(h16, W_Z); h16* __restrict__ cqn = WSP(h16, W_CQN); h16* __restrict__ ckvn = WSP(h16, W_CKVN); h16* __restrict__ knew = WSP(h16, W_KNEW); h16* __restrict__ kb = WSP(h16, W_K); h16* __restrict__ xc = WSP(h16, W_XC);
;             const float* __restrict__ ropec = WSP(float, W_ROPE); const float* __restrict__ ropes = ropec + NPOS * 16;
;             for (int row = gw; row < MT; row += NGW) {
;                 const h16* zr = z + (size_t)row * ZW; const bool samp = row >= MP; const int rs = row - MP;
;                 const int t = samp ? (rs & 31) : (row & (SEQ - 1)), bb = samp ? (rs >> 5) : (row >> 11), T = samp ? DSEQ : SEQ;
;                 h2 xq[3];
; #pragma unroll
;                 for (int i = 0; i < 3; ++i) xq[i] = *(const h2*)(zr + 512 + 2 * lane + 128 * i);
;                 const h4 xkv = *(const h4*)(zr + 896 + 4 * lane);
;                 const int pidx = samp ? SEQ + t : t, l16 = lane & 15;
;                 const float rc = ropec[pidx * 16 + l16], rsn = ropes[pidx * 16 + l16], kx1 = (float)zr[1152 + l16], kx2 = (float)zr[1168 + l16];
;                 const int c = 4 * lane; f4 xl[4];
;     ...
;                 { const float rr = rsqrtf(ssq * (1.f / 384.f) + 1e-6f);
; #pragma unroll
;                   for (int i = 0; i < 3; ++i) { const int cc = 2 * lane + 128 * i; h2 o; o[0] = (h16)(vq[2 * i] * rr * qn_g[cc]); o[1] = (h16)(vq[2 * i + 1] * rr * qn_g[cc + 1]); *(h2*)(cqn + (size_t)row * 384 + cc) = o; } }
;                 { const float rr = rsqrtf(sskv * (1.f / 256.f) + 1e-6f); const f4 v = vkv * rr * *(const f4*)(kvn_g + 4 * lane);
;                   if (!samp) { __builtin_nontemporal_store(v, (f4*)(out + O_PLAT + ((size_t)lq * MP + row) * 256 + 4 * lane)); *(h4*)(ckvn + (size_t)row * 256 + 4 * lane) = pack4(v); }
;                   else { __builtin_nontemporal_store(v, (f4*)(out + O_SLAT + ((size_t)lq * MS + rs) * 256 + 4 * lane)); *(h4*)(knew + (size_t)rs * KNW + 4 * lane) = pack4(v); } }
.LBB0_272:
	s_or_b64 exec, exec, s[0:1]
	s_mov_b32 s0, -1
	s_waitcnt lgkmcnt(0)
	s_barrier
	s_mov_b32 s6, s91
	v_mbcnt_lo_u32_b32 v0, s0, 0
	v_mbcnt_hi_u32_b32 v0, s0, v0
	v_add_u32_e32 v0, s88, v0
	s_mov_b32 s8, s68
	s_mov_b32 s0, s56
	s_lshl_b32 s0, s0, 3
	v_readfirstlane_b32 s1, v0
	s_ashr_i32 s1, s1, 6
	s_add_i32 s0, s0, s1
	s_mov_b64 s[4:5], s[76:77]
	s_cmp_lt_i32 s0, 0x8400
	s_cbranch_scc0 .LBB0_313
	s_load_dwordx4 s[12:15], s[4:5], 0xf8
	s_ashr_i32 s7, s6, 31
	s_lshl_b32 s10, s8, 3
	s_lshl_b64 s[16:17], s[6:7], 5
	s_load_dwordx4 s[24:27], s[4:5], 0xa0
	s_load_dwordx2 s[22:23], s[4:5], 0x78
	s_waitcnt lgkmcnt(0)
	s_add_u32 s28, s14, 0x25e11000
	s_addc_u32 s29, s15, 0
	s_add_u32 s18, s14, 0x24f000
	s_addc_u32 s19, s15, 0
	s_add_u32 s20, s14, 0x26f800
	s_mul_i32 s30, s6, 0x180
	s_load_dwordx2 s[34:35], s[4:5], 0x88
	s_nop 0
	s_load_dwordx2 s[4:5], s[4:5], 0x28
	s_addc_u32 s21, s15, 0
	s_ashr_i32 s31, s30, 31
	s_lshl_b64 s[30:31], s[30:31], 2
	s_add_u32 s30, s22, s30
	s_addc_u32 s31, s23, s31
	s_mul_i32 s9, s6, 0x18000
	s_mul_hi_i32 s1, s6, 0x18000
	s_waitcnt lgkmcnt(0)
	s_add_u32 s4, s4, s9
	s_addc_u32 s5, s5, s1
	s_lshl_b32 s22, s6, 8
	s_ashr_i32 s23, s22, 31
	s_lshl_b64 s[22:23], s[22:23], 2
	s_add_u32 s26, s26, s22
	s_addc_u32 s27, s27, s23
	s_lshl_b64 s[36:37], s[6:7], 12
	s_add_u32 s24, s24, s36
	v_and_b32_e32 v6, 63, v0
	s_addc_u32 s25, s25, s37
	s_add_u32 s22, s34, s22
	v_and_b32_e32 v74, 15, v0
	v_lshlrev_b32_e32 v0, 4, v6
	v_mov_b32_e32 v1, v49
	s_addc_u32 s23, s35, s23
	v_lshl_add_u64 v[36:37], s[4:5], 0, v[0:1]
	s_lshl_b64 s[34:35], s[6:7], 25
	s_lshl_b64 s[4:5], s[6:7], 20
	s_add_u32 s4, s12, s4
	v_lshl_add_u64 v[38:39], s[22:23], 0, v[0:1]
	s_addc_u32 s5, s13, s5
	s_lshl_b64 s[36:37], s[6:7], 22
	s_lshl_b64 s[22:23], s[6:7], 17
	s_add_u32 s22, s12, s22
	v_lshlrev_b32_e32 v2, 2, v6
	v_mov_b32_e32 v3, v49
	v_lshl_add_u64 v[4:5], s[4:5], 0, v[0:1]
	s_mov_b64 s[4:5], 0x11700000
	s_addc_u32 s23, s13, s23
	v_lshlrev_b32_e32 v48, 1, v6
	v_lshl_add_u64 v[40:41], v[4:5], 0, s[4:5]
	v_lshlrev_b32_e32 v4, 3, v6
	v_cmp_gt_u32_e64 s[4:5], 16, v6
	v_lshl_add_u64 v[6:7], s[22:23], 0, v[2:3]
	s_mov_b64 s[22:23], 0x11b00000
	v_lshl_add_u64 v[44:45], v[6:7], 0, s[22:23]
	s_lshl_b64 s[22:23], s[6:7], 4
	s_ashr_i32 s1, s0, 31
	s_mul_hi_i32 s6, s0, 0x300
	s_mul_i32 s7, s0, 0x300
	v_or_b32_e32 v56, s7, v2
	v_mov_b32_e32 v57, s6
	s_lshl_b64 s[6:7], s[0:1], 9
	s_ashr_i32 s11, s10, 31
	v_or_b32_e32 v58, s6, v4
	v_mov_b32_e32 v59, s7
	s_mul_hi_i32 s6, s0, 0x600
	s_mul_i32 s7, s0, 0x600
	v_lshl_add_u64 v[46:47], s[26:27], 0, v[0:1]
	s_lshl_b64 s[26:27], s[10:11], 9
	v_or_b32_e32 v60, s7, v48
	v_mov_b32_e32 v61, s6
	s_lshl_b64 s[6:7], s[0:1], 7
	s_add_u32 s6, s36, s6
	v_mov_b32_e32 v5, v49
	s_addc_u32 s7, s37, s7
	v_lshl_add_u64 v[52:53], s[30:31], 0, v[4:5]
	v_lshl_add_u64 v[62:63], s[6:7], 0, v[2:3]
	s_lshl_b64 s[30:31], s[10:11], 7
	s_lshl_b64 s[6:7], s[0:1], 10
	s_add_u32 s1, s34, s6
	s_addc_u32 s6, s35, s7
	s_add_u32 s1, s1, 0x8400000
	s_addc_u32 s6, s6, 0
	v_or_b32_e32 v64, s1, v0
	v_mov_b32_e32 v65, s6
	s_mul_hi_i32 s1, s0, 0xe00
	s_mul_i32 s6, s0, 0xe00
	v_lshl_add_u64 v[42:43], s[28:29], 0, v[4:5]
	v_lshl_add_u64 v[50:51], s[24:25], 0, v[0:1]
	v_xor_b32_e32 v75, 4, v2
	v_xor_b32_e32 v76, 8, v2
	v_xor_b32_e32 v77, 16, v2
	v_xor_b32_e32 v78, 32, v2
	v_xor_b32_e32 v79, 64, v2
	v_xor_b32_e32 v80, 0x80, v2
	v_lshl_add_u64 v[54:55], s[28:29], 0, v[48:49]
	s_mul_i32 s24, s8, 0x1800
	s_mul_hi_i32 s25, s10, 0x300
	s_mul_i32 s28, s8, 0x3000
	s_mul_hi_i32 s29, s10, 0x600
	s_lshl_b64 s[34:35], s[10:11], 10
	v_or_b32_e32 v66, s6, v4
	v_mov_b32_e32 v67, s1
	s_mul_i32 s36, s8, 0x7000
	s_mul_hi_i32 s37, s10, 0xe00
	v_or_b32_e32 v68, s6, v2
	v_mov_b32_e32 v69, s1
	v_lshl_or_b32 v70, v74, 1, s6
	v_mov_b32_e32 v71, s1
	v_lshlrev_b32_e32 v48, 2, v2
	global_load_dwordx2 v[100:101], v[52:53], off
	global_load_dwordx2 v[102:103], v[52:53], off offset:512
	global_load_dwordx2 v[104:105], v[52:53], off offset:1024
	global_load_dwordx4 v[106:109], v[38:39], off
	global_load_dwordx4 v[110:113], v[46:47], off
	global_load_dwordx4 v[114:117], v[50:51], off
	global_load_dwordx4 v[118:121], v[50:51], off offset:1024
	global_load_dwordx4 v[122:125], v[50:51], off offset:2048
	global_load_dwordx4 v[126:129], v[50:51], off offset:3072
	s_waitcnt vmcnt(0)
	s_branch .LBB0_276

; __global__ void __launch_bounds__(512, 2) trunk_fwd(Params p) {
;     ...
;             for (int row = gw; row < MT; row += NGW) {
;                 const h16* zr = z + (size_t)row * ZW; const bool samp = row >= MP; const int rs = row - MP;
;                 const int t = samp ? (rs & 31) : (row & (SEQ - 1)), bb = samp ? (rs >> 5) : (row >> 11), T = samp ? DSEQ : SEQ;
;                 h2 xq[3];
; #pragma unroll
;                 for (int i = 0; i < 3; ++i) xq[i] = *(const h2*)(zr + 512 + 2 * lane + 128 * i);
;                 const h4 xkv = *(const h4*)(zr + 896 + 4 * lane);
;                 const int pidx = samp ? SEQ + t : t, l16 = lane & 15;
;                 const float rc = ropec[pidx * 16 + l16], rsn = ropes[pidx * 16 + l16], kx1 = (float)zr[1152 + l16], kx2 = (float)zr[1168 + l16];
;                 const int c = 4 * lane; f4 xl[4];
; #pragma unroll
;                 for (int j = 0; j < 4; ++j) { const int tau = t - 3 + j;
;                     if (tau >= 0) { const h4 x = *(const h4*)(zr - (ptrdiff_t)(3 - j) * ZW + 1184 + c); xl[j] = (f4){(float)x[0], (float)x[1], (float)x[2], (float)x[3]}; }
;                     else if (samp) xl[j] = *(const f4*)(stc + ((size_t)bb * 3 + (3 + tau)) * 256 + c);
;                     else xl[j] = (f4){0.f, 0.f, 0.f, 0.f}; }
;     ...
;                 { f4 accv = *(const f4*)(cb + c);
; #pragma unroll
;                   for (int j = 0; j < 4; ++j) accv += xl[j] * *(const f4*)(cw + j * 256 + c);
;                   if (t >= T - 3) { float* o = samp ? out + O_SLC + (((size_t)lq * DBATCH + bb) * 3 + (t - (T - 3))) * 256 : out + O_PLC + (((size_t)lq * NB + bb) * 3 + (t - (T - 3))) * 256; *(f4*)(o + c) = xl[3]; }
;                   *(h4*)(xc + (size_t)row * 256 + c) = pack4(accv); }
.LBB0_275:
	v_pk_fma_f32 v[2:3], v[2:3], v[116:117], v[112:113]
	v_pk_fma_f32 v[0:1], v[0:1], v[114:115], v[110:111]
	v_pk_fma_f32 v[2:3], v[6:7], v[120:121], v[2:3]
	v_pk_fma_f32 v[0:1], v[4:5], v[118:119], v[0:1]
	v_pk_fma_f32 v[2:3], v[10:11], v[124:125], v[2:3]
	v_pk_fma_f32 v[0:1], v[8:9], v[122:123], v[0:1]
	v_pk_fma_f32 v[2:3], v[14:15], v[128:129], v[2:3]
	v_pk_fma_f32 v[0:1], v[12:13], v[126:127], v[0:1]
	s_mov_b32 s1, 0x14511000
	v_cvt_pk_f16_f32 v3, v2, v3
	v_cvt_pk_f16_f32 v2, v0, v1
	v_add_co_u32_e32 v0, vcc, s1, v72
	s_add_i32 s0, s0, s10
	s_nop 0
	v_addc_co_u32_e32 v1, vcc, 0, v73, vcc
	v_lshl_add_u64 v[56:57], v[56:57], 0, s[24:25]
	v_lshl_add_u64 v[58:59], v[58:59], 0, s[26:27]
	v_lshl_add_u64 v[60:61], v[60:61], 0, s[28:29]
	v_lshl_add_u64 v[62:63], v[62:63], 0, s[30:31]
	v_lshl_add_u64 v[64:65], v[64:65], 0, s[34:35]
	v_lshl_add_u64 v[66:67], v[66:67], 0, s[36:37]
	v_lshl_add_u64 v[68:69], v[68:69], 0, s[36:37]
	s_cmp_gt_i32 s0, 0x83ff
	v_lshl_add_u64 v[70:71], v[70:71], 0, s[36:37]
	global_store_dwordx2 v[0:1], v[2:3], off
	s_cbranch_scc1 .LBB0_313
.LBB0_276:
	s_cmpk_gt_i32 s0, 0x7fff
	s_cselect_b64 s[6:7], -1, 0
	s_and_b64 s[6:7], s[6:7], exec
	s_cselect_b32 s1, 31, 0x7ff
	s_and_b32 s1, s1, s0
	s_lshl_b32 s8, s1, 4
	s_or_b32 s9, s8, 0x8000
	s_cmpk_gt_i32 s0, 0x7fff
	s_cselect_b64 s[38:39], -1, 0
	v_lshl_add_u64 v[0:1], s[14:15], 0, v[68:69]
	s_and_b64 s[6:7], s[38:39], exec
	v_add_co_u32_e32 v0, vcc, s80, v0
	s_cselect_b32 s6, s9, s8
	s_nop 0
	v_addc_co_u32_e32 v1, vcc, 0, v1, vcc
	v_lshl_add_u64 v[12:13], s[14:15], 0, v[66:67]
	v_add_co_u32_e32 v2, vcc, s80, v12
	v_or_b32_e32 v4, s6, v74
	s_nop 0
	v_addc_co_u32_e32 v3, vcc, 0, v13, vcc
	v_lshlrev_b32_e32 v6, 2, v4
	v_lshl_add_u64 v[4:5], s[14:15], 0, v[70:71]
	v_add_co_u32_e32 v4, vcc, 0xa8d1000, v4
	s_cmp_lt_i32 s0, 0x8000
	s_nop 0
	v_addc_co_u32_e32 v5, vcc, 0, v5, vcc
	global_load_dword v17, v[0:1], off offset:1024
	global_load_dword v18, v[0:1], off offset:1280
	global_load_dword v16, v[0:1], off offset:1536
	global_load_dwordx2 v[14:15], v[2:3], off offset:1792
	global_load_dword v20, v6, s[18:19]
	global_load_dword v21, v6, s[20:21]
	global_load_ushort v22, v[4:5], off offset:2304
	global_load_ushort v23, v[4:5], off offset:2336
	v_add_co_u32_e32 v130, vcc, 0xa8d1000, v12
	s_nop 1
	v_addc_co_u32_e32 v131, vcc, 0, v13, vcc
	global_load_dwordx2 v[132:133], v[130:131], off offset:2368
	s_cselect_b64 s[40:41], -1, 0
	s_add_i32 s74, s0, 0xffff8000
	s_ashr_i32 s11, s74, 5
	s_mul_i32 s8, s11, 3
	s_ashr_i32 s9, s8, 31
	s_cmp_lt_u32 s1, 3
	s_mov_b64 s[6:7], -1
	s_cbranch_scc0 .Lp2_fast
	s_and_b64 vcc, exec, s[40:41]
	s_cbranch_vccz .LBB0_279
	s_mov_b64 s[6:7], 0

; __global__ void __launch_bounds__(512, 2) trunk_fwd(Params p) {
;     ...
;                 for (int j = 0; j < 4; ++j) { const int tau = t - 3 + j;
;                     if (tau >= 0) { const h4 x = *(const h4*)(zr - (ptrdiff_t)(3 - j) * ZW + 1184 + c); xl[j] = (f4){(float)x[0], (float)x[1], (float)x[2], (float)x[3]}; }
;                     else if (samp) xl[j] = *(const f4*)(stc + ((size_t)bb * 3 + (3 + tau)) * 256 + c);
;                     else xl[j] = (f4){0.f, 0.f, 0.f, 0.f}; }
.Lp2_fast:
	v_add_co_u32_e32 v0, vcc, 0xa8ce000, v12
	s_nop 1
	v_addc_co_u32_e32 v1, vcc, 0, v13, vcc
	global_load_dwordx2 v[2:3], v[0:1], off offset:3904
	v_add_co_u32_e32 v4, vcc, 0xa8cf000, v12
	s_nop 1
	v_addc_co_u32_e32 v5, vcc, 0, v13, vcc
	global_load_dwordx2 v[6:7], v[4:5], off offset:3392
	v_add_co_u32_e32 v8, vcc, 0xa8d0000, v12
	s_nop 1
	v_addc_co_u32_e32 v9, vcc, 0, v13, vcc
	global_load_dwordx2 v[10:11], v[8:9], off offset:2880
	s_andn2_b64 s[6:7], exec, s[40:41]
	s_mov_b64 s[42:43], -1
	s_waitcnt vmcnt(0)
	v_cvt_f32_f16_e32 v0, v2
	v_cvt_f32_f16_sdwa v1, v2 dst_sel:DWORD dst_unused:UNUSED_PAD src0_sel:WORD_1
	v_cvt_f32_f16_e32 v2, v3
	v_cvt_f32_f16_sdwa v3, v3 dst_sel:DWORD dst_unused:UNUSED_PAD src0_sel:WORD_1
	v_cvt_f32_f16_e32 v4, v6
	v_cvt_f32_f16_sdwa v5, v6 dst_sel:DWORD dst_unused:UNUSED_PAD src0_sel:WORD_1
	v_cvt_f32_f16_e32 v6, v7
	v_cvt_f32_f16_sdwa v7, v7 dst_sel:DWORD dst_unused:UNUSED_PAD src0_sel:WORD_1
	v_cvt_f32_f16_e32 v8, v10
	v_cvt_f32_f16_sdwa v9, v10 dst_sel:DWORD dst_unused:UNUSED_PAD src0_sel:WORD_1
	v_cvt_f32_f16_e32 v10, v11
	v_cvt_f32_f16_sdwa v11, v11 dst_sel:DWORD dst_unused:UNUSED_PAD src0_sel:WORD_1
	s_branch .LBB0_299

; DEVI float shx(float v, int o, int lane) { return __builtin_bit_cast(float, __builtin_amdgcn_ds_bpermute((lane ^ o) << 2, __builtin_bit_cast(int, v))); }
; __global__ void __launch_bounds__(512, 2) trunk_fwd(Params p) {
;     ...
;                 float vq[6], ssq = 0.f, sskv = 0.f; f4 vkv;
; #pragma unroll
;                 for (int i = 0; i < 3; ++i) { vq[2 * i] = (float)xq[i][0]; vq[2 * i + 1] = (float)xq[i][1]; ssq += vq[2 * i] * vq[2 * i] + vq[2 * i + 1] * vq[2 * i + 1]; }
; #pragma unroll
;                 for (int e = 0; e < 4; ++e) { vkv[e] = (float)xkv[e]; sskv += vkv[e] * vkv[e]; }
; #pragma unroll
;                 for (int o = 1; o < 64; o <<= 1) { ssq += shx(ssq, o, lane); sskv += shx(sskv, o, lane); }
;                 { const float rr = rsqrtf(ssq * (1.f / 384.f) + 1e-6f);
; #pragma unroll
;                   for (int i = 0; i < 3; ++i) { const int cc = 2 * lane + 128 * i; h2 o; o[0] = (h16)(vq[2 * i] * rr * qn_g[cc]); o[1] = (h16)(vq[2 * i + 1] * rr * qn_g[cc + 1]); *(h2*)(cqn + (size_t)row * 384 + cc) = o; } }
;                 { const float rr = rsqrtf(sskv * (1.f / 256.f) + 1e-6f); const f4 v = vkv * rr * *(const f4*)(kvn_g + 4 * lane);
;                   if (!samp) { __builtin_nontemporal_store(v, (f4*)(out + O_PLAT + ((size_t)lq * MP + row) * 256 + 4 * lane)); *(h4*)(ckvn + (size_t)row * 256 + 4 * lane) = pack4(v); }
.LBB0_299:
	s_waitcnt vmcnt(4)
	v_cvt_f32_f16_sdwa v25, v14 dst_sel:DWORD dst_unused:UNUSED_PAD src0_sel:WORD_1
	v_cvt_f32_f16_e32 v24, v14
	v_cvt_f32_f16_sdwa v27, v15 dst_sel:DWORD dst_unused:UNUSED_PAD src0_sel:WORD_1
	v_cvt_f32_f16_e32 v26, v15
	v_cvt_f32_f16_e32 v32, v17
	v_cvt_f32_f16_e32 v34, v16
	v_cvt_f32_f16_sdwa v19, v18 dst_sel:DWORD dst_unused:UNUSED_PAD src0_sel:WORD_1
	v_cvt_f32_f16_e32 v18, v18
	v_cvt_f32_f16_sdwa v33, v17 dst_sel:DWORD dst_unused:UNUSED_PAD src0_sel:WORD_1
	v_cvt_f32_f16_sdwa v35, v16 dst_sel:DWORD dst_unused:UNUSED_PAD src0_sel:WORD_1
	v_mov_b32_e32 v16, v32
	v_mov_b32_e32 v17, v34
	v_pk_mul_f32 v[28:29], v[24:25], v[24:25]
	v_pk_mul_f32 v[72:73], v[18:19], v[18:19]
	v_pk_mul_f32 v[16:17], v[16:17], v[16:17]
	v_mov_b32_e32 v82, v33
	v_mov_b32_e32 v83, v35
	v_pk_mul_f32 v[30:31], v[26:27], v[26:27]
	v_pk_fma_f32 v[16:17], v[82:83], v[82:83], v[16:17]
	v_mov_b32_e32 v82, v28
	v_mov_b32_e32 v83, v73
	v_pk_mov_b32 v[28:29], v[28:29], v[72:73] op_sel:[1,0]
	v_mov_b32_e32 v72, v30
	v_pk_add_f32 v[28:29], v[82:83], v[28:29]
	v_mov_b32_e32 v73, v16
	v_pk_add_f32 v[28:29], v[28:29], v[72:73]
	v_mov_b32_e32 v16, v31
	v_pk_add_f32 v[16:17], v[28:29], v[16:17]
	ds_bpermute_b32 v28, v75, v16
	ds_bpermute_b32 v29, v75, v17
	v_add_co_u32_e32 v12, vcc, 0xa8d1000, v12
	v_lshl_add_u64 v[30:31], s[14:15], 0, v[56:57]
	s_nop 0
	v_addc_co_u32_e32 v13, vcc, 0, v13, vcc
	s_waitcnt lgkmcnt(0)
	v_pk_add_f32 v[16:17], v[16:17], v[28:29]
	ds_bpermute_b32 v28, v76, v16
	ds_bpermute_b32 v29, v76, v17
	s_mov_b32 s8, 0x11c51000
	v_add_co_u32_e64 v30, s[8:9], s8, v30
	s_mov_b64 s[42:43], -1
	s_waitcnt lgkmcnt(0)
	v_pk_add_f32 v[16:17], v[16:17], v[28:29]
	ds_bpermute_b32 v28, v77, v16
	ds_bpermute_b32 v29, v77, v17
	v_addc_co_u32_e64 v31, s[8:9], 0, v31, s[8:9]
	v_lshl_add_u64 v[72:73], s[14:15], 0, v[58:59]
	s_waitcnt lgkmcnt(0)
	v_pk_add_f32 v[16:17], v[16:17], v[28:29]
	ds_bpermute_b32 v28, v78, v16
	ds_bpermute_b32 v29, v78, v17
	s_waitcnt lgkmcnt(0)
	v_pk_add_f32 v[16:17], v[16:17], v[28:29]
	ds_bpermute_b32 v28, v79, v16
	ds_bpermute_b32 v29, v79, v17
	s_waitcnt lgkmcnt(0)
	v_pk_add_f32 v[16:17], v[16:17], v[28:29]
	ds_bpermute_b32 v28, v80, v16
	ds_bpermute_b32 v29, v80, v17
	s_waitcnt lgkmcnt(0)
	v_pk_add_f32 v[16:17], v[16:17], v[28:29]
	v_mov_b32_e32 v28, 0x358637bd
	v_pk_fma_f32 v[28:29], v[16:17], s[84:85], v[28:29] op_sel_hi:[1,1,0]
	s_nop 0
	v_mul_f32_e32 v16, 0x4b800000, v29
	v_cmp_gt_f32_e32 vcc, s69, v29
	v_cmp_gt_f32_e64 s[8:9], s69, v28
	s_nop 0
	v_cndmask_b32_e32 v16, v29, v16, vcc
	v_rsq_f32_e32 v29, v16
	v_mul_f32_e32 v12, 0x45800000, v29
	v_cndmask_b32_e32 v12, v29, v12, vcc
	v_pk_mul_f32 v[32:33], v[12:13], v[32:33] op_sel_hi:[0,1]
	v_pk_mul_f32 v[14:15], v[32:33], v[100:101]
	s_and_b64 vcc, exec, s[6:7]
	v_cvt_pk_f16_f32 v13, v14, v15
	global_store_dword v[30:31], v13, off
	v_pk_mul_f32 v[18:19], v[12:13], v[18:19] op_sel_hi:[0,1]
	v_pk_mul_f32 v[14:15], v[18:19], v[102:103]
	s_nop 0
	v_cvt_pk_f16_f32 v13, v14, v15
	global_store_dword v[30:31], v13, off offset:256
	v_pk_mul_f32 v[12:13], v[12:13], v[34:35] op_sel_hi:[0,1]
	v_mul_f32_e32 v18, 0x4b800000, v28
	v_cndmask_b32_e64 v18, v28, v18, s[8:9]
	v_rsq_f32_e32 v18, v18
	v_pk_mul_f32 v[12:13], v[12:13], v[104:105]
	s_nop 0
	v_cvt_pk_f16_f32 v12, v12, v13
	global_store_dword v[30:31], v12, off offset:512
	v_mul_f32_e32 v19, 0x45800000, v18
	v_cndmask_b32_e64 v18, v18, v19, s[8:9]
	v_pk_mul_f32 v[26:27], v[26:27], v[18:19] op_sel_hi:[1,0]
	v_pk_mul_f32 v[18:19], v[24:25], v[18:19] op_sel_hi:[1,0]
	s_waitcnt vmcnt(3)
	v_pk_mul_f32 v[14:15], v[26:27], v[108:109]
	v_pk_mul_f32 v[12:13], v[18:19], v[106:107]
	v_cvt_pk_f16_f32 v19, v14, v15
	v_cvt_pk_f16_f32 v18, v12, v13
	s_cbranch_vccnz .LBB0_302
	v_lshl_add_u64 v[24:25], s[12:13], 0, v[64:65]
	global_store_dwordx4 v[24:25], v[12:15], off nt
	v_add_co_u32_e32 v24, vcc, 0x13511000, v72
	s_nop 1
	v_addc_co_u32_e32 v25, vcc, 0, v73, vcc
	global_store_dwordx2 v[24:25], v[18:19], off
	s_cbranch_execz .LBB0_303

; __global__ void __launch_bounds__(512, 2) trunk_fwd(Params p) {
;     ...
;                 { f4 accv = *(const f4*)(cb + c);
; #pragma unroll
;                   for (int j = 0; j < 4; ++j) accv += xl[j] * *(const f4*)(cw + j * 256 + c);
;                   if (t >= T - 3) { float* o = samp ? out + O_SLC + (((size_t)lq * DBATCH + bb) * 3 + (t - (T - 3))) * 256 : out + O_PLC + (((size_t)lq * NB + bb) * 3 + (t - (T - 3))) * 256; *(f4*)(o + c) = xl[3]; }
.LBB0_308:
	s_or_b64 exec, exec, s[8:9]
	v_cvt_f32_f16_sdwa v13, v132 dst_sel:DWORD dst_unused:UNUSED_PAD src0_sel:WORD_1
	v_cvt_f32_f16_e32 v12, v132
	v_cvt_f32_f16_sdwa v15, v133 dst_sel:DWORD dst_unused:UNUSED_PAD src0_sel:WORD_1
	v_cvt_f32_f16_e32 v14, v133
	s_and_b64 s[6:7], s[38:39], exec
	s_cselect_b32 s6, 29, 0x7fd
	s_cmp_lt_u32 s1, s6
	s_cbranch_scc1 .LBB0_275
	s_mov_b64 s[8:9], -1
	s_and_b64 vcc, exec, s[40:41]
	s_cbranch_vccz .LBB0_311
	s_ashr_i32 s6, s0, 11
	s_ashr_i32 s7, s6, 31
	s_add_u32 s6, s22, s6
	s_addc_u32 s7, s23, s7
	s_mul_i32 s7, s7, 3
	s_mul_hi_u32 s8, s6, 3
	s_add_i32 s8, s8, s7
	s_add_i32 s7, s1, 0xfffff803
	s_mul_i32 s6, s6, 3
	s_ashr_i32 s9, s7, 31
	s_add_u32 s6, s6, s7
	s_addc_u32 s7, s8, s9
	s_mov_b64 s[8:9], 0

; #define LAS __attribute__((address_space(3)))
; __global__ void __launch_bounds__(512, 2) trunk_fwd(Params p) {
;     ...
;                     const int it = item - N_SA - N_PA, b = it >> 3, ch = (it & 7) * 32 + (ln & 31), seg = wave * 2 + (ln >> 5), tl = seg * 32 + (ln & 31);
;                     const size_t rbase = (size_t)b * SEQ + seg * 128;
;                     float A = 1.f, B = 0.f;
; #pragma unroll 16
;                     for (int i = 0; i < 128; ++i) { const float a = abuf[(rbase + i) * 256 + ch], bb = bbuf[(rbase + i) * 256 + ch]; B = a * B + bb; A *= a; }
;                     LAS float* sA = (LAS float*)lds; LAS float* sB = sA + 512;
;                     sA[tl] = A; sB[tl] = B;
.LBB0_863:
	v_lshl_add_u64 v[6:7], v[4:5], 0, s[0:1]
	s_add_u32 s0, s0, 0x4000
	s_addc_u32 s1, s1, 0
	v_add_co_u32_e32 v132, vcc, 0x1d591000, v6
	s_nop 1
	v_addc_co_u32_e32 v133, vcc, 0, v7, vcc
	v_add_co_u32_e32 v140, vcc, 0x1f691000, v6
	s_nop 1
	v_addc_co_u32_e32 v141, vcc, 0, v7, vcc
	v_add_co_u32_e32 v134, vcc, 0x1d592000, v6
	s_nop 1
	v_addc_co_u32_e32 v135, vcc, 0, v7, vcc
	v_add_co_u32_e32 v142, vcc, 0x1f692000, v6
	s_nop 1
	v_addc_co_u32_e32 v143, vcc, 0, v7, vcc
	v_add_co_u32_e32 v136, vcc, 0x1d593000, v6
	s_nop 1
	v_addc_co_u32_e32 v137, vcc, 0, v7, vcc
	v_add_co_u32_e32 v144, vcc, 0x1f693000, v6
	s_nop 1
	v_addc_co_u32_e32 v145, vcc, 0, v7, vcc
	v_add_co_u32_e32 v138, vcc, 0x1d594000, v6
	s_nop 1
	v_addc_co_u32_e32 v139, vcc, 0, v7, vcc
	v_add_co_u32_e32 v146, vcc, 0x1f694000, v6
	s_nop 1
	v_addc_co_u32_e32 v147, vcc, 0, v7, vcc
	global_load_dword v100, v[132:133], off
	global_load_dword v116, v[140:141], off
	global_load_dword v101, v[132:133], off offset:1024
	global_load_dword v117, v[140:141], off offset:1024
	global_load_dword v102, v[132:133], off offset:2048
	global_load_dword v118, v[140:141], off offset:2048
	global_load_dword v103, v[132:133], off offset:3072
	global_load_dword v119, v[140:141], off offset:3072
	global_load_dword v104, v[134:135], off
	global_load_dword v120, v[142:143], off
	global_load_dword v105, v[134:135], off offset:1024
	global_load_dword v121, v[142:143], off offset:1024
	global_load_dword v106, v[134:135], off offset:2048
	global_load_dword v122, v[142:143], off offset:2048
	global_load_dword v107, v[134:135], off offset:3072
	global_load_dword v123, v[142:143], off offset:3072
	global_load_dword v108, v[136:137], off
	global_load_dword v124, v[144:145], off
	global_load_dword v109, v[136:137], off offset:1024
	global_load_dword v125, v[144:145], off offset:1024
	global_load_dword v110, v[136:137], off offset:2048
	global_load_dword v126, v[144:145], off offset:2048
	global_load_dword v111, v[136:137], off offset:3072
	global_load_dword v127, v[144:145], off offset:3072
	global_load_dword v112, v[138:139], off
	global_load_dword v128, v[146:147], off
	global_load_dword v113, v[138:139], off offset:1024
	global_load_dword v129, v[146:147], off offset:1024
	global_load_dword v114, v[138:139], off offset:2048
	global_load_dword v130, v[146:147], off offset:2048
	global_load_dword v115, v[138:139], off offset:3072
	global_load_dword v131, v[146:147], off offset:3072
	s_waitcnt vmcnt(0)
	v_fma_f32 v10, v10, v100, v116
	v_mul_f32_e32 v12, v12, v100
	v_fma_f32 v10, v10, v101, v117
	v_mul_f32_e32 v12, v12, v101
	v_fma_f32 v10, v10, v102, v118
	v_mul_f32_e32 v12, v12, v102
	v_fma_f32 v10, v10, v103, v119
	v_mul_f32_e32 v12, v12, v103
	v_fma_f32 v10, v10, v104, v120
	v_mul_f32_e32 v12, v12, v104
	v_fma_f32 v10, v10, v105, v121
	v_mul_f32_e32 v12, v12, v105
	v_fma_f32 v10, v10, v106, v122
	v_mul_f32_e32 v12, v12, v106
	v_fma_f32 v10, v10, v107, v123
	v_mul_f32_e32 v12, v12, v107
	v_fma_f32 v10, v10, v108, v124
	v_mul_f32_e32 v12, v12, v108
	v_fma_f32 v10, v10, v109, v125
	v_mul_f32_e32 v12, v12, v109
	v_fma_f32 v10, v10, v110, v126
	v_mul_f32_e32 v12, v12, v110
	v_fma_f32 v10, v10, v111, v127
	v_mul_f32_e32 v12, v12, v111
	v_fma_f32 v10, v10, v112, v128
	v_mul_f32_e32 v12, v12, v112
	v_fma_f32 v10, v10, v113, v129
	v_mul_f32_e32 v12, v12, v113
	v_fma_f32 v10, v10, v114, v130
	v_mul_f32_e32 v12, v12, v114
	v_fma_f32 v10, v10, v115, v131
	v_mul_f32_e32 v12, v12, v115
	s_cmp_eq_u32 s0, 0x20000
	s_cbranch_scc0 .LBB0_863
	v_lshlrev_b32_e32 v4, 2, v11
	v_lshl_or_b32 v4, v1, 7, v4
	v_add_u32_e32 v4, 16, v4
	ds_write2st64_b32 v4, v12, v10 offset1:8
	v_cmp_lt_i32_e32 vcc, 0, v1
	v_mov_b32_e32 v10, 0
	s_waitcnt lgkmcnt(0)
	s_barrier
	s_and_saveexec_b64 s[0:1], vcc
	s_cbranch_execz .LBB0_868
	v_lshl_add_u32 v4, v11, 2, 16
	v_mov_b32_e32 v10, 0
	s_mov_b64 s[6:7], 0
	v_mov_b32_e32 v5, v1
